# adds: rstd table fill loads the row word once before the loop (was re-loaded and waited per unit); rstd_pass issues its 4 partial-sum loads together; layer-0 census check issues its 16 loads together
# speedup vs baseline: 1.0077x; 1.0036x over previous
; __device__ __forceinline__ int tid_fresh(int wave_s) { int t = wave_s * 64 + (int)__builtin_amdgcn_mbcnt_hi(~0u, __builtin_amdgcn_mbcnt_lo(~0u, 0u)); asm volatile("" : "+v"(t)); return t; }
; __device__ __forceinline__ unsigned xb_ld(unsigned* p)              { return __hip_atomic_load(p, __ATOMIC_RELAXED, __HIP_MEMORY_SCOPE_AGENT); }
; __device__ __forceinline__ CParams kp() { CParams q = (CParams)__builtin_amdgcn_kernarg_segment_ptr(); asm volatile("" : "+s"(q)); return q; }
; __global__ void __launch_bounds__(NTHREADS, 2) fwd_megakernel(Params p_unused) {
;     ...
;             if (tid_fresh(wave_s) == 0) { unsigned* bar = (unsigned*)(kp()->ws + WS_CTL); bool ok = true;
;                 for (unsigned jj = 0; jj < 16; ++jj) ok = ok && (xb_ld(&bar[XB_XCNT(jj)]) == (jj < 8 ? 32u : 0u));
;                 unsigned bx_ = blockIdx.x; asm volatile("" : "+s"(bx_));
;                 if (ok) CTLW_[4] = 1u; else { CTLW_[2] = bx_ % 8u; CTLW_[3] = bx_ / 8u; CTLW_[4] = 0u; } }
.LBB0_124:
	s_or_b64 exec, exec, s[8:9]
	s_cmp_lg_u32 s68, 0
	s_waitcnt lgkmcnt(0)
	s_barrier
	s_cbranch_scc1 .LBB0_146
	v_mov_b32_e32 v0, v208
	s_nop 0
	v_cmp_eq_u32_e32 vcc, 0, v0
	s_and_saveexec_b64 s[8:9], vcc
	s_cbranch_execz .LBB0_145
	s_mov_b64 s[10:11], s[58:59]
	s_load_dwordx2 s[10:11], s[10:11], 0x98
	v_mov_b32_e32 v0, 0x40c00000
	s_mov_b64 s[12:13], 0
	s_waitcnt lgkmcnt(0)
	v_mov_b32_e32 v229, 0x40c01000
	global_load_dword v230, v0, s[10:11] offset:1024 sc1
	global_load_dword v231, v0, s[10:11] offset:1280 sc1
	global_load_dword v232, v0, s[10:11] offset:1536 sc1
	global_load_dword v233, v0, s[10:11] offset:1792 sc1
	global_load_dword v234, v0, s[10:11] offset:2048 sc1
	global_load_dword v235, v0, s[10:11] offset:2304 sc1
	global_load_dword v236, v0, s[10:11] offset:2560 sc1
	global_load_dword v237, v0, s[10:11] offset:2816 sc1
	global_load_dword v238, v0, s[10:11] offset:3072 sc1
	global_load_dword v239, v0, s[10:11] offset:3328 sc1
	global_load_dword v240, v0, s[10:11] offset:3584 sc1
	global_load_dword v241, v0, s[10:11] offset:3840 sc1
	global_load_dword v242, v229, s[10:11] sc1
	global_load_dword v243, v229, s[10:11] offset:256 sc1
	global_load_dword v244, v229, s[10:11] offset:512 sc1
	global_load_dword v245, v229, s[10:11] offset:768 sc1
	s_waitcnt vmcnt(0)
	s_mov_b32 s11, 1
	v_readfirstlane_b32 s10, v230
	s_nop 3
	s_cmp_lg_u32 s10, 32
	s_cselect_b32 s11, 0, s11
	v_readfirstlane_b32 s10, v231
	s_nop 3
	s_cmp_lg_u32 s10, 32
	s_cselect_b32 s11, 0, s11
	v_readfirstlane_b32 s10, v232
	s_nop 3
	s_cmp_lg_u32 s10, 32
	s_cselect_b32 s11, 0, s11
	v_readfirstlane_b32 s10, v233
	s_nop 3
	s_cmp_lg_u32 s10, 32
	s_cselect_b32 s11, 0, s11
	v_readfirstlane_b32 s10, v234
	s_nop 3
	s_cmp_lg_u32 s10, 32
	s_cselect_b32 s11, 0, s11
	v_readfirstlane_b32 s10, v235
	s_nop 3
	s_cmp_lg_u32 s10, 32
	s_cselect_b32 s11, 0, s11
	v_readfirstlane_b32 s10, v236
	s_nop 3
	s_cmp_lg_u32 s10, 32
	s_cselect_b32 s11, 0, s11
	v_readfirstlane_b32 s10, v237
	s_nop 3
	s_cmp_lg_u32 s10, 32
	s_cselect_b32 s11, 0, s11
	v_readfirstlane_b32 s10, v238
	s_nop 3
	s_cmp_lg_u32 s10, 0
	s_cselect_b32 s11, 0, s11
	v_readfirstlane_b32 s10, v239
	s_nop 3
	s_cmp_lg_u32 s10, 0
	s_cselect_b32 s11, 0, s11
	v_readfirstlane_b32 s10, v240
	s_nop 3
	s_cmp_lg_u32 s10, 0
	s_cselect_b32 s11, 0, s11
	v_readfirstlane_b32 s10, v241
	s_nop 3
	s_cmp_lg_u32 s10, 0
	s_cselect_b32 s11, 0, s11
	v_readfirstlane_b32 s10, v242
	s_nop 3
	s_cmp_lg_u32 s10, 0
	s_cselect_b32 s11, 0, s11
	v_readfirstlane_b32 s10, v243
	s_nop 3
	s_cmp_lg_u32 s10, 0
	s_cselect_b32 s11, 0, s11
	v_readfirstlane_b32 s10, v244
	s_nop 3
	s_cmp_lg_u32 s10, 0
	s_cselect_b32 s11, 0, s11
	v_readfirstlane_b32 s10, v245
	s_nop 3
	s_cmp_lg_u32 s10, 0
	s_cselect_b32 s11, 0, s11
	s_cmp_lg_u32 s11, 0
	s_cselect_b64 s[12:13], -1, 0

; #define LAS __attribute__((address_space(3)))
; template <class Epi, bool KREV = false>
; __device__ __forceinline__ void gemm_phase(LAS unsigned char* lds, const Gemm g, const StaticOrder& S, const Epi& E, int wave_s) {
;     ...
;     if constexpr (Epi::RSTD) {
;         LAS float* tab = (LAS float*)(lds + RTAB_OFF);
;         for (int idx = tid; idx < 11 * 256; idx += 512) { Unit uu; if (S.next(idx >> 8, uu)) tab[idx] = E.rstd[uu.pm * BM + (idx & 255)]; }
;         asm volatile("s_waitcnt vmcnt(0) lgkmcnt(0)" ::: "memory"); __builtin_amdgcn_s_barrier(); asm volatile("" ::: "memory");
.LBB0_150:
	v_mov_b32_e32 v8, v208
	s_cmp_ge_i32 s28, s1
	v_readfirstlane_b32 s18, v8
	s_cbranch_scc1 .LBB0_169
	s_movk_i32 s8, 0xb00
	s_and_b32 s17, s28, 7
	v_cmp_gt_i32_e32 vcc, s8, v8
	s_and_saveexec_b64 s[8:9], vcc
	s_cbranch_execz .LBB0_156
	s_lshl_b32 s80, s68, 15
	s_lshl_b64 s[10:11], s[80:81], 2
	s_add_u32 s10, s12, s10
	s_addc_u32 s11, s13, s11
	s_lshl_b32 s14, s16, 11
	s_lshl_b32 s15, s17, 8
	s_or_b32 s14, s15, s14
	v_or_b32_sdwa v0, v8, s14 dst_sel:DWORD dst_unused:UNUSED_PAD src0_sel:BYTE_0 src1_sel:DWORD
	v_ashrrev_i32_e32 v1, 31, v0
	v_lshl_add_u64 v[0:1], v[0:1], 2, s[10:11]
	s_mov_b64 s[10:11], 0x43404000
	v_lshl_add_u64 v[0:1], v[0:1], 0, s[10:11]
	v_readlane_b32 s10, v255, 30
	v_mov_b32_e32 v3, v8
	s_nop 0
	v_lshl_add_u32 v2, v8, 2, s10
	s_mov_b64 s[10:11], 0
	global_load_dword v230, v[0:1], off
	s_waitcnt vmcnt(0)
	s_branch .LBB0_154

; template <class Epi, bool KREV = false>
; __device__ __forceinline__ void gemm_phase(LAS unsigned char* lds, const Gemm g, const StaticOrder& S, const Epi& E, int wave_s) {
;     ...
;         for (int idx = tid; idx < 11 * 256; idx += 512) { Unit uu; if (S.next(idx >> 8, uu)) tab[idx] = E.rstd[uu.pm * BM + (idx & 255)]; }
.LBB0_154:
	v_ashrrev_i32_e32 v4, 3, v3
	v_and_b32_e32 v4, 0xffffffe0, v4
	v_add_u32_e32 v4, s28, v4
	v_cmp_gt_i32_e32 vcc, s1, v4
	s_and_saveexec_b64 s[14:15], vcc
	s_cbranch_execz .LBB0_153
	ds_write_b32 v2, v230
	s_branch .LBB0_153

; template <int M> __device__ __forceinline__ float shx(float v) { return __int_as_float(__builtin_amdgcn_ds_swizzle(__float_as_int(v), (M << 10) | 0x1f)); }
; __device__ __forceinline__ void rstd_pass(const float* Pg, float* rstdg, int gtid, int gthreads, int tok0) {
;     ...
;     for (int r = gtid >> 3; r < SEQ; r += gthreads >> 3) {
;         const int part = gtid & 7; float sq = 0.f;
; #pragma unroll
;         for (int i = 0; i < 4; ++i) sq += P[(size_t)(part * 4 + i) * MT + r];
;         sq += shx<1>(sq); sq += shx<2>(sq); sq += shx<4>(sq);
;         if (part == 0) rstd[r] = rsqrtf(sq * (1.f / DM) + EPS);
;     }
.LBB0_748:
	s_waitcnt lgkmcnt(0)
	v_lshl_add_u64 v[8:9], v[0:1], 0, s[10:11]
	global_load_dword v7, v[8:9], off
	v_lshl_add_u64 v[8:9], v[2:3], 0, s[10:11]
	v_add_co_u32_e32 v10, vcc, 0x42414000, v8
	s_nop 1
	v_addc_co_u32_e32 v11, vcc, 0, v9, vcc
	global_load_dword v230, v[10:11], off
	v_add_co_u32_e32 v10, vcc, 0x42424000, v8
	s_nop 1
	v_addc_co_u32_e32 v11, vcc, 0, v9, vcc
	v_add_co_u32_e32 v8, vcc, 0x42434000, v8
	global_load_dword v10, v[10:11], off
	s_nop 0
	v_addc_co_u32_e32 v9, vcc, 0, v9, vcc
	global_load_dword v8, v[8:9], off
	s_waitcnt vmcnt(3)
	v_add_f32_e32 v7, 0, v7
	s_waitcnt vmcnt(2)
	v_add_f32_e32 v7, v7, v230
	s_waitcnt vmcnt(1)
	v_add_f32_e32 v7, v7, v10
	s_waitcnt vmcnt(0)
	v_add_f32_e32 v7, v7, v8
	ds_swizzle_b32 v8, v7 offset:swizzle(SWAP,1)
	s_waitcnt lgkmcnt(0)
	v_add_f32_e32 v7, v7, v8
	ds_swizzle_b32 v8, v7 offset:swizzle(SWAP,2)
	s_waitcnt lgkmcnt(0)
	v_add_f32_e32 v7, v7, v8
	ds_swizzle_b32 v8, v7 offset:swizzle(SWAP,4)
	s_and_saveexec_b64 s[14:15], s[4:5]
	s_cbranch_execz .LBB0_747
	s_waitcnt lgkmcnt(0)
	v_add_f32_e32 v7, v7, v8
	v_fmamk_f32 v7, v7, 0x3a000000, v215
	s_mov_b32 s0, 0x800000
	v_mul_f32_e32 v8, 0x4b800000, v7
	v_cmp_gt_f32_e32 vcc, s0, v7
	s_nop 1
	v_cndmask_b32_e32 v7, v7, v8, vcc
	v_rsq_f32_e32 v7, v7
	s_nop 0
	v_mul_f32_e32 v8, 0x45800000, v7
	v_cndmask_b32_e32 v7, v7, v8, vcc
	v_lshl_add_u64 v[8:9], v[4:5], 0, s[10:11]
	global_store_dword v[8:9], v7, off
	s_branch .LBB0_747

; #define LAS __attribute__((address_space(3)))
; template <class Epi, bool KREV = false>
; __device__ __forceinline__ void gemm_phase(LAS unsigned char* lds, const Gemm g, const StaticOrder& S, const Epi& E, int wave_s) {
;     ...
;     if constexpr (Epi::RSTD) {
;         LAS float* tab = (LAS float*)(lds + RTAB_OFF);
;         for (int idx = tid; idx < 11 * 256; idx += 512) { Unit uu; if (S.next(idx >> 8, uu)) tab[idx] = E.rstd[uu.pm * BM + (idx & 255)]; }
;         asm volatile("s_waitcnt vmcnt(0) lgkmcnt(0)" ::: "memory"); __builtin_amdgcn_s_barrier(); asm volatile("" ::: "memory");
.LBB0_824:
	s_mov_b64 s[4:5], s[58:59]
	v_mov_b32_e32 v0, 0x23008
	s_mov_b64 s[8:9], s[58:59]
	v_add_u32_e32 v0, 0, v0
	ds_read_b32 v0, v0
	s_mov_b64 s[12:13], s[58:59]
	v_mov_b32_e32 v8, v208
	s_mul_hi_u32 s15, s68, 0x8400
	s_mul_i32 s14, s68, 0x8400
	s_waitcnt lgkmcnt(0)
	v_readfirstlane_b32 s1, v0
	v_mov_b32_e32 v0, 0x2300c
	s_mul_hi_u32 s17, s68, 0x2c00
	v_add_u32_e32 v0, 0, v0
	ds_read_b32 v0, v0
	s_mul_i32 s16, s68, 0x2c00
	s_waitcnt lgkmcnt(0)
	v_readfirstlane_b32 s61, v0
	v_readfirstlane_b32 s0, v8
	s_cmpk_gt_i32 s61, 0x15f
	s_cbranch_scc1 .LBB0_859
	s_load_dwordx2 s[10:11], s[4:5], 0x98
	s_nop 0
	s_load_dwordx2 s[8:9], s[8:9], 0x78
	s_nop 0
	s_load_dwordx2 s[4:5], s[12:13], 0x80
	s_movk_i32 s12, 0xb00
	s_and_b32 s21, s61, 7
	v_cmp_gt_i32_e32 vcc, s12, v8
	s_and_saveexec_b64 s[12:13], vcc
	s_cbranch_execz .LBB0_830
	s_lshl_b64 s[6:7], s[6:7], 16
	s_waitcnt lgkmcnt(0)
	s_add_u32 s6, s10, s6
	s_addc_u32 s7, s11, s7
	s_lshl_b32 s18, s1, 11
	s_lshl_b32 s19, s21, 8
	s_or_b32 s18, s19, s18
	v_or_b32_sdwa v0, v8, s18 dst_sel:DWORD dst_unused:UNUSED_PAD src0_sel:BYTE_0 src1_sel:DWORD
	v_ashrrev_i32_e32 v1, 31, v0
	v_lshl_add_u64 v[0:1], v[0:1], 2, s[6:7]
	s_mov_b64 s[6:7], 0x43404000
	v_lshl_add_u64 v[0:1], v[0:1], 0, s[6:7]
	v_readlane_b32 s6, v255, 30
	v_mov_b32_e32 v3, v8
	s_nop 0
	v_lshl_add_u32 v2, v8, 2, s6
	s_mov_b64 s[6:7], 0
	global_load_dword v230, v[0:1], off
	s_waitcnt vmcnt(0)
	s_branch .LBB0_828

; template <class Epi, bool KREV = false>
; __device__ __forceinline__ void gemm_phase(LAS unsigned char* lds, const Gemm g, const StaticOrder& S, const Epi& E, int wave_s) {
;     ...
;         for (int idx = tid; idx < 11 * 256; idx += 512) { Unit uu; if (S.next(idx >> 8, uu)) tab[idx] = E.rstd[uu.pm * BM + (idx & 255)]; }
.LBB0_828:
	v_ashrrev_i32_e32 v4, 3, v3
	v_and_b32_e32 v4, 0xffffffe0, v4
	v_add_u32_e32 v4, s61, v4
	s_movk_i32 s18, 0x160
	v_cmp_gt_i32_e32 vcc, s18, v4
	s_and_saveexec_b64 s[18:19], vcc
	s_cbranch_execz .LBB0_827
	ds_write_b32 v2, v230
	s_branch .LBB0_827
